# v22 with the s_mov m0 placed one instruction earlier before the first FF1 I1 LDS-DMA piece (M0 wait-state rule)
# speedup vs baseline: 1.0122x; 1.0038x over previous
.LBB0_211:
	s_add_i32 s73, s58, 2
	s_add_u32 s74, s56, 0x80
	s_addc_u32 s59, s57, 0
	s_add_i32 s78, 0, 0x10000
	s_cmp_eq_u32 s63, s58
	s_cselect_b32 s59, s51, s59
	s_cselect_b32 s58, s55, s74
	v_add_u32_e32 v0, s78, v146
	s_cselect_b32 s75, s45, s72
	s_cselect_b32 s74, s44, s67
	s_add_i32 s80, 0, 0x14000
	ds_read_b128 v[148:151], v0
	ds_read_b128 v[152:155], v0 offset:1024
	ds_read_b128 v[156:159], v0 offset:2048
	ds_read_b128 v[160:163], v0 offset:3072
	v_add_u32_e32 v0, s80, v146
	ds_read_b128 v[164:167], v0
	ds_read_b128 v[168:171], v0 offset:1024
	ds_read_b128 v[172:175], v0 offset:2048
	ds_read_b128 v[176:179], v0 offset:3072
	s_mov_b32 m0, s31
	v_lshl_add_u64 v[142:143], s[56:57], 0, v[136:137]
	global_load_lds_dwordx4 v[142:143], off
	v_lshl_add_u64 v[142:143], s[56:57], 0, v[132:133]
	s_mov_b32 m0, s53
	s_nop 0
	global_load_lds_dwordx4 v[142:143], off
	v_lshl_add_u64 v[142:143], s[56:57], 0, v[138:139]
	s_add_i32 m0, s27, 0xc000
	s_nop 0
	global_load_lds_dwordx4 v[142:143], off
	v_lshl_add_u64 v[142:143], s[56:57], 0, v[140:141]
	s_add_i32 m0, s27, 0xe000
	s_nop 0
	global_load_lds_dwordx4 v[142:143], off
	ds_read_b128 v[180:183], v147
	ds_read_b128 v[184:187], v147 offset:1024
	ds_read_b128 v[200:203], v147 offset:2048
	ds_read_b128 v[204:207], v147 offset:3072
	ds_read_b128 v[208:211], v147 offset:4096
	ds_read_b128 v[212:215], v147 offset:5120
	ds_read_b128 v[216:219], v147 offset:6144
	ds_read_b128 v[220:223], v147 offset:7168
	s_waitcnt vmcnt(8)
	s_waitcnt lgkmcnt(0)
	s_barrier
	s_setprio 1
	s_waitcnt lgkmcnt(0)
	v_mfma_f32_16x16x32_bf16 v[122:125], v[148:151], v[180:183], v[122:125]
	v_mfma_f32_16x16x32_bf16 v[126:129], v[156:159], v[180:183], v[126:129]
	v_mfma_f32_16x16x32_bf16 v[110:113], v[148:151], v[200:203], v[110:113]
	v_mfma_f32_16x16x32_bf16 v[106:109], v[156:159], v[200:203], v[106:109]
	v_mfma_f32_16x16x32_bf16 v[94:97], v[148:151], v[208:211], v[94:97]
	v_mfma_f32_16x16x32_bf16 v[90:93], v[156:159], v[208:211], v[90:93]
	v_mfma_f32_16x16x32_bf16 v[78:81], v[148:151], v[216:219], v[78:81]
	v_mfma_f32_16x16x32_bf16 v[74:77], v[156:159], v[216:219], v[74:77]
	v_mfma_f32_16x16x32_bf16 v[122:125], v[152:155], v[184:187], v[122:125]
	v_mfma_f32_16x16x32_bf16 v[126:129], v[160:163], v[184:187], v[126:129]
	v_mfma_f32_16x16x32_bf16 v[110:113], v[152:155], v[204:207], v[110:113]
	v_mfma_f32_16x16x32_bf16 v[106:109], v[160:163], v[204:207], v[106:109]
	v_mfma_f32_16x16x32_bf16 v[94:97], v[152:155], v[212:215], v[94:97]
	v_mfma_f32_16x16x32_bf16 v[90:93], v[160:163], v[212:215], v[90:93]
	v_mfma_f32_16x16x32_bf16 v[78:81], v[152:155], v[220:223], v[78:81]
	v_mfma_f32_16x16x32_bf16 v[74:77], v[160:163], v[220:223], v[74:77]
	s_setprio 0
	s_setprio 1
	v_mfma_f32_16x16x32_bf16 v[118:121], v[164:167], v[180:183], v[118:121]
	v_mfma_f32_16x16x32_bf16 v[114:117], v[172:175], v[180:183], v[114:117]
	v_mfma_f32_16x16x32_bf16 v[102:105], v[164:167], v[200:203], v[102:105]
	v_mfma_f32_16x16x32_bf16 v[98:101], v[172:175], v[200:203], v[98:101]
	v_mfma_f32_16x16x32_bf16 v[86:89], v[164:167], v[208:211], v[86:89]
	v_mfma_f32_16x16x32_bf16 v[82:85], v[172:175], v[208:211], v[82:85]
	v_mfma_f32_16x16x32_bf16 v[70:73], v[164:167], v[216:219], v[70:73]
	v_mfma_f32_16x16x32_bf16 v[66:69], v[172:175], v[216:219], v[66:69]
	v_mfma_f32_16x16x32_bf16 v[118:121], v[168:171], v[184:187], v[118:121]
	v_mfma_f32_16x16x32_bf16 v[114:117], v[176:179], v[184:187], v[114:117]
	v_mfma_f32_16x16x32_bf16 v[102:105], v[168:171], v[204:207], v[102:105]
	v_mfma_f32_16x16x32_bf16 v[98:101], v[176:179], v[204:207], v[98:101]
	v_mfma_f32_16x16x32_bf16 v[86:89], v[168:171], v[212:215], v[86:89]
	v_mfma_f32_16x16x32_bf16 v[82:85], v[176:179], v[212:215], v[82:85]
	v_mfma_f32_16x16x32_bf16 v[70:73], v[168:171], v[220:223], v[70:73]
	v_mfma_f32_16x16x32_bf16 v[66:69], v[176:179], v[220:223], v[66:69]
	s_setprio 0
	s_barrier
	s_add_i32 s78, s78, s5
	v_lshl_add_u64 v[142:143], s[74:75], 0, v[134:135]
	s_mov_b32 m0, s78
	ds_read_b128 v[180:183], v147 offset:16384
	ds_read_b128 v[184:187], v147 offset:17408
	ds_read_b128 v[200:203], v147 offset:18432
	ds_read_b128 v[204:207], v147 offset:19456
	ds_read_b128 v[208:211], v147 offset:20480
	ds_read_b128 v[212:215], v147 offset:21504
	ds_read_b128 v[216:219], v147 offset:22528
	ds_read_b128 v[220:223], v147 offset:23552
	global_load_lds_dwordx4 v[142:143], off
	s_add_i32 m0, s78, 0x2000
	v_lshl_add_u64 v[188:189], s[74:75], 0, v[130:131]
	s_add_u32 s74, s74, s6
	s_addc_u32 s75, s75, s7
	s_add_i32 s78, s80, s5
	global_load_lds_dwordx4 v[188:189], off
	v_lshl_add_u64 v[224:225], s[74:75], 0, v[134:135]
	s_mov_b32 m0, s78
	v_lshl_add_u64 v[226:227], s[74:75], 0, v[130:131]
	global_load_lds_dwordx4 v[224:225], off
	s_add_i32 m0, s78, 0x2000
	v_lshl_add_u64 v[228:229], s[58:59], 0, v[136:137]
	global_load_lds_dwordx4 v[226:227], off
	v_lshl_add_u64 v[230:231], s[58:59], 0, v[132:133]
	s_waitcnt vmcnt(6)
	s_waitcnt lgkmcnt(0)
	s_barrier
	s_setprio 1
	s_waitcnt lgkmcnt(0)
	v_mfma_f32_16x16x32_bf16 v[62:65], v[148:151], v[180:183], v[62:65]
	v_mfma_f32_16x16x32_bf16 v[58:61], v[156:159], v[180:183], v[58:61]
	v_mfma_f32_16x16x32_bf16 v[46:49], v[148:151], v[200:203], v[46:49]
	v_mfma_f32_16x16x32_bf16 v[42:45], v[156:159], v[200:203], v[42:45]
	v_mfma_f32_16x16x32_bf16 v[30:33], v[148:151], v[208:211], v[30:33]
	v_mfma_f32_16x16x32_bf16 v[26:29], v[156:159], v[208:211], v[26:29]
	v_mfma_f32_16x16x32_bf16 v[14:17], v[148:151], v[216:219], v[14:17]
	v_mfma_f32_16x16x32_bf16 v[10:13], v[156:159], v[216:219], v[10:13]
	v_mfma_f32_16x16x32_bf16 v[62:65], v[152:155], v[184:187], v[62:65]
	v_mfma_f32_16x16x32_bf16 v[58:61], v[160:163], v[184:187], v[58:61]
	v_mfma_f32_16x16x32_bf16 v[46:49], v[152:155], v[204:207], v[46:49]
	v_mfma_f32_16x16x32_bf16 v[42:45], v[160:163], v[204:207], v[42:45]
	v_mfma_f32_16x16x32_bf16 v[30:33], v[152:155], v[212:215], v[30:33]
	v_mfma_f32_16x16x32_bf16 v[26:29], v[160:163], v[212:215], v[26:29]
	v_mfma_f32_16x16x32_bf16 v[14:17], v[152:155], v[220:223], v[14:17]
	v_mfma_f32_16x16x32_bf16 v[10:13], v[160:163], v[220:223], v[10:13]
	s_setprio 0
	s_setprio 1
	v_mfma_f32_16x16x32_bf16 v[54:57], v[164:167], v[180:183], v[54:57]
	v_mfma_f32_16x16x32_bf16 v[50:53], v[172:175], v[180:183], v[50:53]
	v_mfma_f32_16x16x32_bf16 v[38:41], v[164:167], v[200:203], v[38:41]
	v_mfma_f32_16x16x32_bf16 v[34:37], v[172:175], v[200:203], v[34:37]
	v_mfma_f32_16x16x32_bf16 v[22:25], v[164:167], v[208:211], v[22:25]
	v_mfma_f32_16x16x32_bf16 v[18:21], v[172:175], v[208:211], v[18:21]
	v_mfma_f32_16x16x32_bf16 v[6:9], v[164:167], v[216:219], v[6:9]
	v_mfma_f32_16x16x32_bf16 v[2:5], v[172:175], v[216:219], v[2:5]
	v_mfma_f32_16x16x32_bf16 v[54:57], v[168:171], v[184:187], v[54:57]
	v_mfma_f32_16x16x32_bf16 v[50:53], v[176:179], v[184:187], v[50:53]
	v_mfma_f32_16x16x32_bf16 v[38:41], v[168:171], v[204:207], v[38:41]
	v_mfma_f32_16x16x32_bf16 v[34:37], v[176:179], v[204:207], v[34:37]
	v_mfma_f32_16x16x32_bf16 v[22:25], v[168:171], v[212:215], v[22:25]
	v_mfma_f32_16x16x32_bf16 v[18:21], v[176:179], v[212:215], v[18:21]
	v_mfma_f32_16x16x32_bf16 v[6:9], v[168:171], v[220:223], v[6:9]
	v_mfma_f32_16x16x32_bf16 v[2:5], v[176:179], v[220:223], v[2:5]
	s_setprio 0
	s_barrier
	s_add_i32 s74, 0, 0x18000
	v_add_u32_e32 v0, s74, v146
	s_add_i32 s75, 0, 0x1c000
	ds_read_b128 v[148:151], v0
	ds_read_b128 v[152:155], v0 offset:1024
	ds_read_b128 v[156:159], v0 offset:2048
	ds_read_b128 v[160:163], v0 offset:3072
	v_add_u32_e32 v0, s75, v146
	ds_read_b128 v[164:167], v0
	ds_read_b128 v[168:171], v0 offset:1024
	ds_read_b128 v[172:175], v0 offset:2048
	ds_read_b128 v[176:179], v0 offset:3072
	s_add_u32 s58, s58, s2
	s_addc_u32 s59, s59, s3
	s_mov_b32 m0, s27
	v_lshl_add_u64 v[232:233], s[58:59], 0, v[136:137]
	s_nop 0
	global_load_lds_dwordx4 v[228:229], off
	s_mov_b32 m0, s28
	s_nop 0
	global_load_lds_dwordx4 v[230:231], off
	s_mov_b32 m0, s29
	s_nop 0
	global_load_lds_dwordx4 v[232:233], off
	v_lshl_add_u64 v[232:233], s[58:59], 0, v[132:133]
	s_mov_b32 m0, s30
	s_nop 0
	global_load_lds_dwordx4 v[232:233], off
	ds_read_b128 v[180:183], v147 offset:32768
	ds_read_b128 v[184:187], v147 offset:33792
	ds_read_b128 v[200:203], v147 offset:34816
	ds_read_b128 v[204:207], v147 offset:35840
	ds_read_b128 v[208:211], v147 offset:36864
	ds_read_b128 v[212:215], v147 offset:37888
	ds_read_b128 v[216:219], v147 offset:38912
	ds_read_b128 v[220:223], v147 offset:39936
	s_waitcnt vmcnt(8)
	s_waitcnt lgkmcnt(0)
	s_barrier
	s_setprio 1
	s_waitcnt lgkmcnt(0)
	v_mfma_f32_16x16x32_bf16 v[122:125], v[148:151], v[180:183], v[122:125]
	v_mfma_f32_16x16x32_bf16 v[126:129], v[156:159], v[180:183], v[126:129]
	v_mfma_f32_16x16x32_bf16 v[110:113], v[148:151], v[200:203], v[110:113]
	v_mfma_f32_16x16x32_bf16 v[106:109], v[156:159], v[200:203], v[106:109]
	v_mfma_f32_16x16x32_bf16 v[94:97], v[148:151], v[208:211], v[94:97]
	v_mfma_f32_16x16x32_bf16 v[90:93], v[156:159], v[208:211], v[90:93]
	v_mfma_f32_16x16x32_bf16 v[78:81], v[148:151], v[216:219], v[78:81]
	v_mfma_f32_16x16x32_bf16 v[74:77], v[156:159], v[216:219], v[74:77]
	v_mfma_f32_16x16x32_bf16 v[122:125], v[152:155], v[184:187], v[122:125]
	v_mfma_f32_16x16x32_bf16 v[126:129], v[160:163], v[184:187], v[126:129]
	v_mfma_f32_16x16x32_bf16 v[110:113], v[152:155], v[204:207], v[110:113]
	v_mfma_f32_16x16x32_bf16 v[106:109], v[160:163], v[204:207], v[106:109]
	v_mfma_f32_16x16x32_bf16 v[94:97], v[152:155], v[212:215], v[94:97]
	v_mfma_f32_16x16x32_bf16 v[90:93], v[160:163], v[212:215], v[90:93]
	v_mfma_f32_16x16x32_bf16 v[78:81], v[152:155], v[220:223], v[78:81]
	v_mfma_f32_16x16x32_bf16 v[74:77], v[160:163], v[220:223], v[74:77]
	s_setprio 0
	s_setprio 1
	v_mfma_f32_16x16x32_bf16 v[118:121], v[164:167], v[180:183], v[118:121]
	v_mfma_f32_16x16x32_bf16 v[114:117], v[172:175], v[180:183], v[114:117]
	v_mfma_f32_16x16x32_bf16 v[102:105], v[164:167], v[200:203], v[102:105]
	v_mfma_f32_16x16x32_bf16 v[98:101], v[172:175], v[200:203], v[98:101]
	v_mfma_f32_16x16x32_bf16 v[86:89], v[164:167], v[208:211], v[86:89]
	v_mfma_f32_16x16x32_bf16 v[82:85], v[172:175], v[208:211], v[82:85]
	v_mfma_f32_16x16x32_bf16 v[70:73], v[164:167], v[216:219], v[70:73]
	v_mfma_f32_16x16x32_bf16 v[66:69], v[172:175], v[216:219], v[66:69]
	v_mfma_f32_16x16x32_bf16 v[118:121], v[168:171], v[184:187], v[118:121]
	v_mfma_f32_16x16x32_bf16 v[114:117], v[176:179], v[184:187], v[114:117]
	v_mfma_f32_16x16x32_bf16 v[102:105], v[168:171], v[204:207], v[102:105]
	v_mfma_f32_16x16x32_bf16 v[98:101], v[176:179], v[204:207], v[98:101]
	v_mfma_f32_16x16x32_bf16 v[86:89], v[168:171], v[212:215], v[86:89]
	v_mfma_f32_16x16x32_bf16 v[82:85], v[176:179], v[212:215], v[82:85]
	v_mfma_f32_16x16x32_bf16 v[70:73], v[168:171], v[220:223], v[70:73]
	v_mfma_f32_16x16x32_bf16 v[66:69], v[176:179], v[220:223], v[66:69]
	s_setprio 0
	s_barrier
	s_add_i32 s58, s74, s5
	v_lshl_add_u64 v[142:143], v[142:143], 0, s[24:25]
	s_mov_b32 m0, s58
	ds_read_b128 v[180:183], v147 offset:49152
	ds_read_b128 v[184:187], v147 offset:50176
	ds_read_b128 v[200:203], v147 offset:51200
	ds_read_b128 v[204:207], v147 offset:52224
	ds_read_b128 v[208:211], v147 offset:53248
	ds_read_b128 v[212:215], v147 offset:54272
	ds_read_b128 v[216:219], v147 offset:55296
	ds_read_b128 v[220:223], v147 offset:56320
	global_load_lds_dwordx4 v[142:143], off
	v_lshl_add_u64 v[142:143], v[188:189], 0, s[24:25]
	s_add_i32 m0, s58, 0x2000
	s_add_i32 s58, s75, s5
	global_load_lds_dwordx4 v[142:143], off
	v_lshl_add_u64 v[142:143], v[224:225], 0, s[24:25]
	s_mov_b32 m0, s58
	s_nop 0
	global_load_lds_dwordx4 v[142:143], off
	v_lshl_add_u64 v[142:143], v[226:227], 0, s[24:25]
	s_add_i32 m0, s58, 0x2000
	s_nop 0
	global_load_lds_dwordx4 v[142:143], off
	s_waitcnt vmcnt(6)
	s_waitcnt lgkmcnt(0)
	s_barrier
	s_setprio 1
	s_waitcnt lgkmcnt(0)
	v_mfma_f32_16x16x32_bf16 v[62:65], v[148:151], v[180:183], v[62:65]
	v_mfma_f32_16x16x32_bf16 v[58:61], v[156:159], v[180:183], v[58:61]
	v_mfma_f32_16x16x32_bf16 v[46:49], v[148:151], v[200:203], v[46:49]
	v_mfma_f32_16x16x32_bf16 v[42:45], v[156:159], v[200:203], v[42:45]
	v_mfma_f32_16x16x32_bf16 v[30:33], v[148:151], v[208:211], v[30:33]
	v_mfma_f32_16x16x32_bf16 v[26:29], v[156:159], v[208:211], v[26:29]
	v_mfma_f32_16x16x32_bf16 v[14:17], v[148:151], v[216:219], v[14:17]
	v_mfma_f32_16x16x32_bf16 v[10:13], v[156:159], v[216:219], v[10:13]
	v_mfma_f32_16x16x32_bf16 v[62:65], v[152:155], v[184:187], v[62:65]
	v_mfma_f32_16x16x32_bf16 v[58:61], v[160:163], v[184:187], v[58:61]
	v_mfma_f32_16x16x32_bf16 v[46:49], v[152:155], v[204:207], v[46:49]
	v_mfma_f32_16x16x32_bf16 v[42:45], v[160:163], v[204:207], v[42:45]
	v_mfma_f32_16x16x32_bf16 v[30:33], v[152:155], v[212:215], v[30:33]
	v_mfma_f32_16x16x32_bf16 v[26:29], v[160:163], v[212:215], v[26:29]
	v_mfma_f32_16x16x32_bf16 v[14:17], v[152:155], v[220:223], v[14:17]
	v_mfma_f32_16x16x32_bf16 v[10:13], v[160:163], v[220:223], v[10:13]
	s_setprio 0
	s_setprio 1
	v_mfma_f32_16x16x32_bf16 v[54:57], v[164:167], v[180:183], v[54:57]
	v_mfma_f32_16x16x32_bf16 v[50:53], v[172:175], v[180:183], v[50:53]
	v_mfma_f32_16x16x32_bf16 v[38:41], v[164:167], v[200:203], v[38:41]
	v_mfma_f32_16x16x32_bf16 v[34:37], v[172:175], v[200:203], v[34:37]
	v_mfma_f32_16x16x32_bf16 v[22:25], v[164:167], v[208:211], v[22:25]
	v_mfma_f32_16x16x32_bf16 v[18:21], v[172:175], v[208:211], v[18:21]
	v_mfma_f32_16x16x32_bf16 v[6:9], v[164:167], v[216:219], v[6:9]
	v_mfma_f32_16x16x32_bf16 v[2:5], v[172:175], v[216:219], v[2:5]
	v_mfma_f32_16x16x32_bf16 v[54:57], v[168:171], v[184:187], v[54:57]
	v_mfma_f32_16x16x32_bf16 v[50:53], v[176:179], v[184:187], v[50:53]
	v_mfma_f32_16x16x32_bf16 v[38:41], v[168:171], v[204:207], v[38:41]
	v_mfma_f32_16x16x32_bf16 v[34:37], v[176:179], v[204:207], v[34:37]
	v_mfma_f32_16x16x32_bf16 v[22:25], v[168:171], v[212:215], v[22:25]
	v_mfma_f32_16x16x32_bf16 v[18:21], v[176:179], v[212:215], v[18:21]
	v_mfma_f32_16x16x32_bf16 v[6:9], v[168:171], v[220:223], v[6:9]
	v_mfma_f32_16x16x32_bf16 v[2:5], v[176:179], v[220:223], v[2:5]
	s_setprio 0
	s_barrier
	s_add_u32 s56, s56, 0x100
	s_addc_u32 s57, s57, 0
	s_add_u32 s67, s67, 0x100
	s_addc_u32 s72, s72, 0
	s_cmp_ge_i32 s73, s60
	s_mov_b32 s58, s73
	s_cbranch_scc0 .LBB0_211
	v_readlane_b32 s74, v236, 30
	v_readlane_b32 s75, v236, 31
	v_readlane_b32 s73, v236, 32
	s_mov_b32 s78, s76
